# prep loop (a): sc_b/sc_z row loads issued with the first six loads of the item (one HBM round trip per item instead of two)
# speedup vs baseline: 1.0090x; 1.0001x over previous
.LBB0_315:
	s_or_b64 exec, exec, s[0:1]
	global_load_dwordx4 v[100:103], v[26:27], off offset:512
	global_load_dwordx4 v[104:107], v[26:27], off offset:1536
	v_readlane_b32 s0, v254, 48
	v_mov_b32_e32 v39, v9
	v_readlane_b32 s1, v254, 49
	s_waitcnt vmcnt(3)
	v_lshlrev_b32_e32 v28, 16, v18
	v_and_b32_e32 v29, 0xffff0000, v18
	v_lshl_add_u64 v[32:33], s[0:1], 0, v[38:39]
	s_waitcnt vmcnt(2)
	v_lshlrev_b32_e32 v30, 16, v22
	v_and_b32_e32 v31, 0xffff0000, v22
	v_lshlrev_b32_e32 v60, 16, v19
	v_and_b32_e32 v61, 0xffff0000, v19
	v_lshlrev_b32_e32 v48, 16, v20
	v_and_b32_e32 v49, 0xffff0000, v20
	v_lshlrev_b32_e32 v38, 16, v21
	v_and_b32_e32 v39, 0xffff0000, v21
	v_lshlrev_b32_e32 v18, 16, v4
	v_and_b32_e32 v19, 0xffff0000, v4
	v_lshlrev_b32_e32 v20, 16, v14
	v_and_b32_e32 v21, 0xffff0000, v14
	v_lshlrev_b32_e32 v66, 16, v23
	v_and_b32_e32 v67, 0xffff0000, v23
	v_lshlrev_b32_e32 v52, 16, v24
	v_and_b32_e32 v53, 0xffff0000, v24
	v_lshlrev_b32_e32 v42, 16, v25
	v_and_b32_e32 v43, 0xffff0000, v25
	v_lshlrev_b32_e32 v70, 16, v10
	v_and_b32_e32 v71, 0xffff0000, v10
	v_lshlrev_b32_e32 v62, 16, v11
	v_and_b32_e32 v63, 0xffff0000, v11
	v_lshlrev_b32_e32 v50, 16, v12
	v_and_b32_e32 v51, 0xffff0000, v12
	v_lshlrev_b32_e32 v40, 16, v13
	v_and_b32_e32 v41, 0xffff0000, v13
	v_lshlrev_b32_e32 v64, 16, v5
	v_and_b32_e32 v65, 0xffff0000, v5
	v_lshlrev_b32_e32 v54, 16, v6
	v_and_b32_e32 v55, 0xffff0000, v6
	v_lshlrev_b32_e32 v44, 16, v7
	v_and_b32_e32 v45, 0xffff0000, v7
	v_lshlrev_b32_e32 v68, 16, v15
	v_and_b32_e32 v69, 0xffff0000, v15
	v_lshlrev_b32_e32 v56, 16, v16
	v_and_b32_e32 v57, 0xffff0000, v16
	v_lshlrev_b32_e32 v46, 16, v17
	v_and_b32_e32 v47, 0xffff0000, v17
	s_waitcnt vmcnt(0)
	v_mov_b64_e32 v[10:11], v[100:101]
	v_mov_b64_e32 v[12:13], v[102:103]
	v_mov_b64_e32 v[4:5], v[104:105]
	v_mov_b64_e32 v[6:7], v[106:107]
	v_pk_mul_f32 v[22:23], v[20:21], v[30:31]
	global_load_dwordx4 v[14:17], v[32:33], off offset:16
	global_load_dwordx4 v[24:27], v[32:33], off
	v_pk_mul_f32 v[34:35], v[18:19], v[28:29]
	global_load_dwordx4 v[18:21], v[32:33], off offset:1040
	global_load_dwordx4 v[28:31], v[32:33], off offset:1024
	v_lshlrev_b32_e32 v78, 16, v0
	v_and_b32_e32 v79, 0xffff0000, v0
	v_pk_mul_f32 v[70:71], v[70:71], v[78:79]
	v_pk_mul_f32 v[60:61], v[64:65], v[60:61]
	v_ashrrev_i32_e32 v37, 31, v36
	v_add_u32_e32 v74, s26, v74
	s_waitcnt vmcnt(5)
	v_lshlrev_b32_e32 v80, 16, v10
	s_waitcnt vmcnt(4)
	v_lshlrev_b32_e32 v0, 16, v4
	v_and_b32_e32 v81, 0xffff0000, v10
	v_and_b32_e32 v4, 0xffff0000, v4
	v_mul_f32_e32 v10, 0xbfb8aa3b, v0
	s_waitcnt vmcnt(0)
	v_pk_mul_f32 v[22:23], v[22:23], v[28:29]
	v_exp_f32_e32 v82, v10
	v_pk_fma_f32 v[28:29], v[34:35], v[24:25], v[22:23]
	global_load_dwordx4 v[22:25], v[32:33], off offset:2064
	s_nop 0
	global_load_dwordx4 v[32:35], v[32:33], off offset:2048
	v_mul_f32_e32 v10, 0xbfb8aa3b, v4
	v_exp_f32_e32 v83, v10
	s_waitcnt vmcnt(0)
	v_pk_fma_f32 v[28:29], v[70:71], v[32:33], v[28:29]
	v_pk_add_f32 v[32:33], v[82:83], 1.0 op_sel_hi:[1,0]
	v_pk_mul_f32 v[28:29], v[28:29], v[80:81]
	v_div_scale_f32 v10, s[0:1], v33, v33, v4
	v_rcp_f32_e32 v70, v10
	s_nop 0
	v_fma_f32 v71, -v10, v70, 1.0
	v_fmac_f32_e32 v70, v71, v70
	v_div_scale_f32 v71, vcc, v4, v33, v4
	v_mul_f32_e32 v73, v71, v70
	v_fma_f32 v75, -v10, v73, v71
	v_fmac_f32_e32 v73, v75, v70
	v_fma_f32 v10, -v10, v73, v71
	v_div_fmas_f32 v10, v10, v70, v73
	v_div_fixup_f32 v33, v10, v33, v4
	v_div_scale_f32 v4, s[0:1], v32, v32, v0
	v_rcp_f32_e32 v10, v4
	s_nop 0
	v_fma_f32 v70, -v4, v10, 1.0
	v_fmac_f32_e32 v10, v70, v10
	v_div_scale_f32 v70, vcc, v0, v32, v0
	v_mul_f32_e32 v71, v70, v10
	v_fma_f32 v73, -v4, v71, v70
	v_fmac_f32_e32 v71, v73, v10
	v_fma_f32 v4, -v4, v71, v70
	v_div_fmas_f32 v4, v4, v10, v71
	v_div_fixup_f32 v32, v4, v32, v0
	v_pk_mul_f32 v[28:29], v[28:29], v[32:33]
	v_pk_mul_f32 v[32:33], v[68:69], v[66:67]
	v_lshlrev_b32_e32 v66, 16, v5
	v_and_b32_e32 v67, 0xffff0000, v5
	v_mul_f32_e32 v4, 0xbfb8aa3b, v66
	v_mul_f32_e32 v5, 0xbfb8aa3b, v67
	v_exp_f32_e32 v4, v4
	v_exp_f32_e32 v5, v5
	v_lshlrev_b32_e32 v0, 16, v1
	v_and_b32_e32 v1, 0xffff0000, v1
	v_pk_mul_f32 v[30:31], v[32:33], v[30:31]
	v_pk_mul_f32 v[0:1], v[62:63], v[0:1]
	v_pk_fma_f32 v[26:27], v[60:61], v[26:27], v[30:31]
	v_lshlrev_b32_e32 v10, 16, v11
	v_and_b32_e32 v11, 0xffff0000, v11
	v_pk_fma_f32 v[0:1], v[0:1], v[34:35], v[26:27]
	v_pk_add_f32 v[4:5], v[4:5], 1.0 op_sel_hi:[1,0]
	v_pk_mul_f32 v[0:1], v[0:1], v[10:11]
	v_div_scale_f32 v10, s[0:1], v5, v5, v67
	v_rcp_f32_e32 v11, v10
	v_pk_mul_f32 v[32:33], v[54:55], v[48:49]
	v_fma_f32 v26, -v10, v11, 1.0
	v_fmac_f32_e32 v11, v26, v11
	v_div_scale_f32 v26, vcc, v67, v5, v67
	v_mul_f32_e32 v27, v26, v11
	v_fma_f32 v30, -v10, v27, v26
	v_fmac_f32_e32 v27, v30, v11
	v_fma_f32 v10, -v10, v27, v26
	v_div_fmas_f32 v10, v10, v11, v27
	v_div_fixup_f32 v5, v10, v5, v67
	v_div_scale_f32 v10, s[0:1], v4, v4, v66
	v_rcp_f32_e32 v11, v10
	s_nop 0
	v_fma_f32 v26, -v10, v11, 1.0
	v_fmac_f32_e32 v11, v26, v11
	v_div_scale_f32 v26, vcc, v66, v4, v66
	v_mul_f32_e32 v27, v26, v11
	v_fma_f32 v30, -v10, v27, v26
	v_fmac_f32_e32 v27, v30, v11
	v_fma_f32 v10, -v10, v27, v26
	v_div_fmas_f32 v10, v10, v11, v27
	v_div_fixup_f32 v4, v10, v4, v66
	v_pk_mul_f32 v[0:1], v[4:5], v[0:1]
	v_pk_mul_f32 v[4:5], v[56:57], v[52:53]
	v_lshlrev_b32_e32 v10, 16, v2
	v_and_b32_e32 v11, 0xffff0000, v2
	v_pk_mul_f32 v[4:5], v[4:5], v[18:19]
	v_lshlrev_b32_e32 v2, 16, v6
	v_and_b32_e32 v6, 0xffff0000, v6
	v_pk_fma_f32 v[4:5], v[32:33], v[14:15], v[4:5]
	v_pk_mul_f32 v[10:11], v[50:51], v[10:11]
	v_lshlrev_b32_e32 v26, 16, v12
	v_and_b32_e32 v27, 0xffff0000, v12
	v_mul_f32_e32 v12, 0xbfb8aa3b, v2
	v_pk_fma_f32 v[4:5], v[10:11], v[22:23], v[4:5]
	v_mul_f32_e32 v10, 0xbfb8aa3b, v6
	v_exp_f32_e32 v30, v12
	v_exp_f32_e32 v31, v10
	v_pk_mul_f32 v[4:5], v[4:5], v[26:27]
	v_pk_add_f32 v[10:11], v[30:31], 1.0 op_sel_hi:[1,0]
	s_nop 0
	v_div_scale_f32 v12, s[0:1], v11, v11, v6
	v_rcp_f32_e32 v14, v12
	s_nop 0
	v_fma_f32 v15, -v12, v14, 1.0
	v_fmac_f32_e32 v14, v15, v14
	v_div_scale_f32 v15, vcc, v6, v11, v6
	v_mul_f32_e32 v18, v15, v14
	v_fma_f32 v19, -v12, v18, v15
	v_fmac_f32_e32 v18, v19, v14
	v_fma_f32 v12, -v12, v18, v15
	v_div_fmas_f32 v12, v12, v14, v18
	v_div_fixup_f32 v11, v12, v11, v6
	v_div_scale_f32 v6, s[0:1], v10, v10, v2
	v_rcp_f32_e32 v12, v6
	v_and_b32_e32 v19, 0xffff0000, v7
	v_fma_f32 v14, -v6, v12, 1.0
	v_fmac_f32_e32 v12, v14, v12
	v_div_scale_f32 v14, vcc, v2, v10, v2
	v_mul_f32_e32 v15, v14, v12
	v_fma_f32 v18, -v6, v15, v14
	v_fmac_f32_e32 v15, v18, v12
	v_fma_f32 v6, -v6, v15, v14
	v_div_fmas_f32 v6, v6, v12, v15
	v_lshlrev_b32_e32 v18, 16, v7
	v_div_fixup_f32 v10, v6, v10, v2
	v_mul_f32_e32 v6, 0xbfb8aa3b, v18
	v_mul_f32_e32 v7, 0xbfb8aa3b, v19
	v_exp_f32_e32 v6, v6
	v_exp_f32_e32 v7, v7
	v_pk_mul_f32 v[4:5], v[10:11], v[4:5]
	v_pk_mul_f32 v[10:11], v[46:47], v[42:43]
	v_lshlrev_b32_e32 v2, 16, v3
	v_and_b32_e32 v3, 0xffff0000, v3
	v_pk_mul_f32 v[14:15], v[44:45], v[38:39]
	v_pk_mul_f32 v[10:11], v[10:11], v[20:21]
	v_pk_mul_f32 v[2:3], v[40:41], v[2:3]
	v_pk_fma_f32 v[10:11], v[14:15], v[16:17], v[10:11]
	v_pk_add_f32 v[6:7], v[6:7], 1.0 op_sel_hi:[1,0]
	v_pk_fma_f32 v[2:3], v[2:3], v[24:25], v[10:11]
	v_div_scale_f32 v10, s[0:1], v7, v7, v19
	v_rcp_f32_e32 v11, v10
	v_lshlrev_b32_e32 v12, 16, v13
	v_and_b32_e32 v13, 0xffff0000, v13
	v_pk_mul_f32 v[2:3], v[2:3], v[12:13]
	v_fma_f32 v12, -v10, v11, 1.0
	v_fmac_f32_e32 v11, v12, v11
	v_div_scale_f32 v12, vcc, v19, v7, v19
	v_mul_f32_e32 v13, v12, v11
	v_fma_f32 v14, -v10, v13, v12
	v_fmac_f32_e32 v13, v14, v11
	v_fma_f32 v10, -v10, v13, v12
	v_div_fmas_f32 v10, v10, v11, v13
	v_div_fixup_f32 v7, v10, v7, v19
	v_div_scale_f32 v10, s[0:1], v6, v6, v18
	v_rcp_f32_e32 v11, v10
	v_readlane_b32 s0, v251, 59
	v_readlane_b32 s1, v251, 60
	v_add_u32_e32 v39, s34, v72
	v_fma_f32 v12, -v10, v11, 1.0
	v_fmac_f32_e32 v11, v12, v11
	v_div_scale_f32 v12, vcc, v18, v6, v18
	v_mul_f32_e32 v13, v12, v11
	v_fma_f32 v14, -v10, v13, v12
	v_fmac_f32_e32 v13, v14, v11
	v_fma_f32 v10, -v10, v13, v12
	v_div_fmas_f32 v10, v10, v11, v13
	v_div_fixup_f32 v6, v10, v6, v18
	v_pk_mul_f32 v[6:7], v[6:7], v[2:3]
	v_cvt_pk_bf16_f32 v3, v0, v1
	v_lshlrev_b64 v[0:1], 11, v[36:37]
	v_lshl_add_u64 v[0:1], s[0:1], 0, v[0:1]
	s_mov_b32 s0, 0x10ffff
	v_cmp_lt_i32_e32 vcc, s0, v39
	v_cvt_pk_bf16_f32 v2, v28, v29
	v_cvt_pk_bf16_f32 v4, v4, v5
	v_cvt_pk_bf16_f32 v5, v6, v7
	v_lshl_add_u64 v[0:1], v[0:1], 0, v[8:9]
	s_orn2_b64 s[0:1], vcc, exec
	global_store_dwordx4 v[0:1], v[2:5], off

.LBB0_325:
	s_or_b64 exec, exec, s[0:1]
	global_load_dwordx4 v[100:103], v[26:27], off offset:512
	global_load_dwordx4 v[104:107], v[26:27], off offset:1536
	v_readlane_b32 s0, v254, 48
	s_waitcnt vmcnt(3)
	v_lshlrev_b32_e32 v28, 16, v18
	v_and_b32_e32 v29, 0xffff0000, v18
	s_waitcnt vmcnt(2)
	v_lshlrev_b32_e32 v32, 16, v22
	v_and_b32_e32 v33, 0xffff0000, v22
	v_lshlrev_b32_e32 v62, 16, v19
	v_and_b32_e32 v63, 0xffff0000, v19
	v_lshlrev_b32_e32 v50, 16, v20
	v_and_b32_e32 v51, 0xffff0000, v20
	v_lshlrev_b32_e32 v40, 16, v21
	v_and_b32_e32 v41, 0xffff0000, v21
	v_lshlrev_b32_e32 v18, 16, v4
	v_and_b32_e32 v19, 0xffff0000, v4
	v_lshlrev_b32_e32 v20, 16, v14
	v_and_b32_e32 v21, 0xffff0000, v14
	v_lshlrev_b32_e32 v38, 2, v30
	v_readlane_b32 s1, v254, 49
	v_lshlrev_b32_e32 v68, 16, v23
	v_and_b32_e32 v69, 0xffff0000, v23
	v_lshlrev_b32_e32 v54, 16, v24
	v_and_b32_e32 v55, 0xffff0000, v24
	v_lshlrev_b32_e32 v44, 16, v25
	v_and_b32_e32 v45, 0xffff0000, v25
	v_lshlrev_b32_e32 v72, 16, v10
	v_and_b32_e32 v73, 0xffff0000, v10
	v_lshlrev_b32_e32 v64, 16, v11
	v_and_b32_e32 v65, 0xffff0000, v11
	v_lshlrev_b32_e32 v52, 16, v12
	v_and_b32_e32 v53, 0xffff0000, v12
	v_lshlrev_b32_e32 v42, 16, v13
	v_and_b32_e32 v43, 0xffff0000, v13
	v_lshlrev_b32_e32 v66, 16, v5
	v_and_b32_e32 v67, 0xffff0000, v5
	v_lshlrev_b32_e32 v56, 16, v6
	v_and_b32_e32 v57, 0xffff0000, v6
	v_lshlrev_b32_e32 v46, 16, v7
	v_and_b32_e32 v47, 0xffff0000, v7
	v_lshlrev_b32_e32 v70, 16, v15
	v_and_b32_e32 v71, 0xffff0000, v15
	v_lshlrev_b32_e32 v60, 16, v16
	v_and_b32_e32 v61, 0xffff0000, v16
	v_lshlrev_b32_e32 v48, 16, v17
	v_and_b32_e32 v49, 0xffff0000, v17
	s_waitcnt vmcnt(0)
	v_mov_b64_e32 v[10:11], v[100:101]
	v_mov_b64_e32 v[12:13], v[102:103]
	v_mov_b64_e32 v[4:5], v[104:105]
	v_mov_b64_e32 v[6:7], v[106:107]
	v_pk_mul_f32 v[22:23], v[20:21], v[32:33]
	global_load_dwordx4 v[14:17], v38, s[0:1] offset:16
	global_load_dwordx4 v[24:27], v38, s[0:1]
	v_pk_mul_f32 v[32:33], v[18:19], v[28:29]
	global_load_dwordx4 v[18:21], v38, s[0:1] offset:1040
	global_load_dwordx4 v[28:31], v38, s[0:1] offset:1024
	v_lshlrev_b32_e32 v78, 16, v0
	v_and_b32_e32 v79, 0xffff0000, v0
	v_pk_mul_f32 v[72:73], v[72:73], v[78:79]
	v_pk_mul_f32 v[62:63], v[66:67], v[62:63]
	v_ashrrev_i32_e32 v37, 31, v36
	s_waitcnt vmcnt(5)
	v_lshlrev_b32_e32 v80, 16, v10
	s_waitcnt vmcnt(4)
	v_lshlrev_b32_e32 v0, 16, v4
	v_and_b32_e32 v81, 0xffff0000, v10
	v_and_b32_e32 v4, 0xffff0000, v4
	v_mul_f32_e32 v10, 0xbfb8aa3b, v0
	s_waitcnt vmcnt(0)
	v_pk_mul_f32 v[22:23], v[22:23], v[28:29]
	v_exp_f32_e32 v82, v10
	v_pk_fma_f32 v[28:29], v[32:33], v[24:25], v[22:23]
	global_load_dwordx4 v[22:25], v38, s[0:1] offset:2064
	global_load_dwordx4 v[32:35], v38, s[0:1] offset:2048
	v_mul_f32_e32 v10, 0xbfb8aa3b, v4
	v_exp_f32_e32 v83, v10
	s_waitcnt vmcnt(0)
	v_pk_fma_f32 v[28:29], v[72:73], v[32:33], v[28:29]
	v_pk_add_f32 v[32:33], v[82:83], 1.0 op_sel_hi:[1,0]
	v_pk_mul_f32 v[28:29], v[28:29], v[80:81]
	v_div_scale_f32 v10, s[0:1], v33, v33, v4
	v_rcp_f32_e32 v72, v10
	s_nop 0
	v_fma_f32 v73, -v10, v72, 1.0
	v_fmac_f32_e32 v72, v73, v72
	v_div_scale_f32 v73, vcc, v4, v33, v4
	v_mul_f32_e32 v75, v73, v72
	v_fma_f32 v77, -v10, v75, v73
	v_fmac_f32_e32 v75, v77, v72
	v_fma_f32 v10, -v10, v75, v73
	v_div_fmas_f32 v10, v10, v72, v75
	v_div_fixup_f32 v33, v10, v33, v4
	v_div_scale_f32 v4, s[0:1], v32, v32, v0
	v_rcp_f32_e32 v10, v4
	s_nop 0
	v_fma_f32 v72, -v4, v10, 1.0
	v_fmac_f32_e32 v10, v72, v10
	v_div_scale_f32 v72, vcc, v0, v32, v0
	v_mul_f32_e32 v73, v72, v10
	v_fma_f32 v75, -v4, v73, v72
	v_fmac_f32_e32 v73, v75, v10
	v_fma_f32 v4, -v4, v73, v72
	v_div_fmas_f32 v4, v4, v10, v73
	v_div_fixup_f32 v32, v4, v32, v0
	v_pk_mul_f32 v[28:29], v[28:29], v[32:33]
	v_pk_mul_f32 v[32:33], v[70:71], v[68:69]
	v_lshlrev_b32_e32 v68, 16, v5
	v_and_b32_e32 v69, 0xffff0000, v5
	v_mul_f32_e32 v4, 0xbfb8aa3b, v68
	v_mul_f32_e32 v5, 0xbfb8aa3b, v69
	v_exp_f32_e32 v4, v4
	v_exp_f32_e32 v5, v5
	v_lshlrev_b32_e32 v0, 16, v1
	v_and_b32_e32 v1, 0xffff0000, v1
	v_pk_mul_f32 v[30:31], v[32:33], v[30:31]
	v_pk_mul_f32 v[0:1], v[64:65], v[0:1]
	v_pk_fma_f32 v[26:27], v[62:63], v[26:27], v[30:31]
	v_lshlrev_b32_e32 v10, 16, v11
	v_and_b32_e32 v11, 0xffff0000, v11
	v_pk_fma_f32 v[0:1], v[0:1], v[34:35], v[26:27]
	v_pk_add_f32 v[4:5], v[4:5], 1.0 op_sel_hi:[1,0]
	v_pk_mul_f32 v[0:1], v[0:1], v[10:11]
	v_div_scale_f32 v10, s[0:1], v5, v5, v69
	v_rcp_f32_e32 v11, v10
	v_pk_mul_f32 v[32:33], v[56:57], v[50:51]
	v_add_u32_e32 v72, s34, v39
	v_fma_f32 v26, -v10, v11, 1.0
	v_fmac_f32_e32 v11, v26, v11
	v_div_scale_f32 v26, vcc, v69, v5, v69
	v_mul_f32_e32 v27, v26, v11
	v_fma_f32 v30, -v10, v27, v26
	v_fmac_f32_e32 v27, v30, v11
	v_fma_f32 v10, -v10, v27, v26
	v_div_fmas_f32 v10, v10, v11, v27
	v_div_fixup_f32 v5, v10, v5, v69
	v_div_scale_f32 v10, s[0:1], v4, v4, v68
	v_rcp_f32_e32 v11, v10
	s_nop 0
	v_fma_f32 v26, -v10, v11, 1.0
	v_fmac_f32_e32 v11, v26, v11
	v_div_scale_f32 v26, vcc, v68, v4, v68
	v_mul_f32_e32 v27, v26, v11
	v_fma_f32 v30, -v10, v27, v26
	v_fmac_f32_e32 v27, v30, v11
	v_fma_f32 v10, -v10, v27, v26
	v_div_fmas_f32 v10, v10, v11, v27
	v_div_fixup_f32 v4, v10, v4, v68
	v_pk_mul_f32 v[0:1], v[4:5], v[0:1]
	v_pk_mul_f32 v[4:5], v[60:61], v[54:55]
	v_lshlrev_b32_e32 v10, 16, v2
	v_and_b32_e32 v11, 0xffff0000, v2
	v_pk_mul_f32 v[4:5], v[4:5], v[18:19]
	v_lshlrev_b32_e32 v2, 16, v6
	v_and_b32_e32 v6, 0xffff0000, v6
	v_pk_fma_f32 v[4:5], v[32:33], v[14:15], v[4:5]
	v_pk_mul_f32 v[10:11], v[52:53], v[10:11]
	v_lshlrev_b32_e32 v26, 16, v12
	v_and_b32_e32 v27, 0xffff0000, v12
	v_mul_f32_e32 v12, 0xbfb8aa3b, v2
	v_pk_fma_f32 v[4:5], v[10:11], v[22:23], v[4:5]
	v_mul_f32_e32 v10, 0xbfb8aa3b, v6
	v_exp_f32_e32 v30, v12
	v_exp_f32_e32 v31, v10
	v_pk_mul_f32 v[4:5], v[4:5], v[26:27]
	v_pk_add_f32 v[10:11], v[30:31], 1.0 op_sel_hi:[1,0]
	s_nop 0
	v_div_scale_f32 v12, s[0:1], v11, v11, v6
	v_rcp_f32_e32 v14, v12
	s_nop 0
	v_fma_f32 v15, -v12, v14, 1.0
	v_fmac_f32_e32 v14, v15, v14
	v_div_scale_f32 v15, vcc, v6, v11, v6
	v_mul_f32_e32 v18, v15, v14
	v_fma_f32 v19, -v12, v18, v15
	v_fmac_f32_e32 v18, v19, v14
	v_fma_f32 v12, -v12, v18, v15
	v_div_fmas_f32 v12, v12, v14, v18
	v_div_fixup_f32 v11, v12, v11, v6
	v_div_scale_f32 v6, s[0:1], v10, v10, v2
	v_rcp_f32_e32 v12, v6
	v_and_b32_e32 v19, 0xffff0000, v7
	v_fma_f32 v14, -v6, v12, 1.0
	v_fmac_f32_e32 v12, v14, v12
	v_div_scale_f32 v14, vcc, v2, v10, v2
	v_mul_f32_e32 v15, v14, v12
	v_fma_f32 v18, -v6, v15, v14
	v_fmac_f32_e32 v15, v18, v12
	v_fma_f32 v6, -v6, v15, v14
	v_div_fmas_f32 v6, v6, v12, v15
	v_lshlrev_b32_e32 v18, 16, v7
	v_div_fixup_f32 v10, v6, v10, v2
	v_mul_f32_e32 v6, 0xbfb8aa3b, v18
	v_mul_f32_e32 v7, 0xbfb8aa3b, v19
	v_exp_f32_e32 v6, v6
	v_exp_f32_e32 v7, v7
	v_pk_mul_f32 v[4:5], v[10:11], v[4:5]
	v_pk_mul_f32 v[10:11], v[48:49], v[44:45]
	v_lshlrev_b32_e32 v2, 16, v3
	v_and_b32_e32 v3, 0xffff0000, v3
	v_pk_mul_f32 v[14:15], v[46:47], v[40:41]
	v_pk_mul_f32 v[10:11], v[10:11], v[20:21]
	v_pk_mul_f32 v[2:3], v[42:43], v[2:3]
	v_pk_fma_f32 v[10:11], v[14:15], v[16:17], v[10:11]
	v_pk_add_f32 v[6:7], v[6:7], 1.0 op_sel_hi:[1,0]
	v_pk_fma_f32 v[2:3], v[2:3], v[24:25], v[10:11]
	v_div_scale_f32 v10, s[0:1], v7, v7, v19
	v_rcp_f32_e32 v11, v10
	v_lshlrev_b32_e32 v12, 16, v13
	v_and_b32_e32 v13, 0xffff0000, v13
	v_pk_mul_f32 v[2:3], v[2:3], v[12:13]
	v_fma_f32 v12, -v10, v11, 1.0
	v_fmac_f32_e32 v11, v12, v11
	v_div_scale_f32 v12, vcc, v19, v7, v19
	v_mul_f32_e32 v13, v12, v11
	v_fma_f32 v14, -v10, v13, v12
	v_fmac_f32_e32 v13, v14, v11
	v_fma_f32 v10, -v10, v13, v12
	v_div_fmas_f32 v10, v10, v11, v13
	v_div_fixup_f32 v7, v10, v7, v19
	v_div_scale_f32 v10, s[0:1], v6, v6, v18
	v_rcp_f32_e32 v11, v10
	v_readlane_b32 s0, v251, 59
	v_readlane_b32 s1, v251, 60
	v_cvt_pk_bf16_f32 v4, v4, v5
	v_fma_f32 v12, -v10, v11, 1.0
	v_fmac_f32_e32 v11, v12, v11
	v_div_scale_f32 v12, vcc, v18, v6, v18
	v_mul_f32_e32 v13, v12, v11
	v_fma_f32 v14, -v10, v13, v12
	v_fmac_f32_e32 v13, v14, v11
	v_fma_f32 v10, -v10, v13, v12
	v_div_fmas_f32 v10, v10, v11, v13
	v_div_fixup_f32 v6, v10, v6, v18
	v_pk_mul_f32 v[6:7], v[6:7], v[2:3]
	v_cvt_pk_bf16_f32 v3, v0, v1
	v_lshlrev_b64 v[0:1], 11, v[36:37]
	v_lshl_add_u64 v[0:1], s[0:1], 0, v[0:1]
	s_mov_b32 s0, 0x110000
	v_cvt_pk_bf16_f32 v2, v28, v29
	v_cvt_pk_bf16_f32 v5, v6, v7
	v_lshl_add_u64 v[0:1], v[0:1], 0, v[8:9]
	v_cmp_gt_i32_e32 vcc, s0, v72
	s_mov_b64 s[0:1], -1
	global_store_dwordx4 v[0:1], v[2:5], off
	s_and_saveexec_b64 s[18:19], vcc
	s_cbranch_execz .LBB0_316
	v_ashrrev_i32_e32 v36, 5, v72
	s_mov_b32 s0, 0x8000
	v_cmp_gt_i32_e32 vcc, s0, v36
	v_mov_b64_e32 v[2:3], s[70:71]
	v_mad_i64_i32 v[2:3], s[2:3], v36, s77, v[2:3]
	v_cndmask_b32_e32 v0, v222, v223, vcc
	v_and_b32_e32 v1, v0, v36
	v_mov_b32_e32 v10, 0
	v_cmp_ne_u32_e64 s[0:1], 0, v1
	v_lshl_add_u64 v[26:27], v[2:3], 0, v[8:9]
	v_mov_b32_e32 v4, 0
	v_mov_b32_e32 v5, 0
	v_mov_b32_e32 v6, 0
	v_mov_b32_e32 v7, 0
	s_and_saveexec_b64 s[4:5], s[0:1]
	s_cbranch_execz .LBB0_328
	v_add_co_u32_e32 v2, vcc, 0xfffff000, v26
	s_nop 1
	v_addc_co_u32_e32 v3, vcc, -1, v27, vcc
	global_load_dwordx4 v[4:7], v[2:3], off offset:-3072
